# combined: EpiResid x-load pipeline depth 6, dilated combine-stage load batching, gemm_in first-iteration peel, barrier first-arriver L2 write-back, rank-discovery load batching
# speedup vs baseline: 1.0034x; 1.0034x over previous
; __device__ __forceinline__ unsigned cvt_pk_bf16(float lo, float hi) { unsigned r; asm volatile("v_cvt_pk_bf16_f32 %0, %1, %2" : "=v"(r) : "v"(lo), "v"(hi)); return r; }
;     __device__ __forceinline__ void operator()(const f32x4 (&acc)[2][2][4][2], const Unit& u, int wr, int wc, int fr, int fq) const {
;     ...
;         for (int ai = 0; ai < 2; ++ai)
; #pragma unroll
;             for (int m = 0; m < 4; ++m) { const size_t row = rowb + ai * HALF + m * 16; const size_t off = row * 1024 + col0; float s = 0.f;
; #pragma unroll
;                 for (int bj = 0; bj < 2; ++bj) { u32x2 w[2];
; #pragma unroll
;                     for (int n = 0; n < 2; ++n) { const f32x4 xv = *(const __attribute__((address_space(1))) f32x4*)(xin + off + bj * HALF + n * 16);
;                         const f32x4 xn = xv + gv[bj][n] * acc[ai][bj][m][n];
;                         *(__attribute__((address_space(1))) f32x4*)(out + off + bj * HALF + n * 16) = xn;
;                         if (XG) { s += (xn[0] * xn[0] + xn[1] * xn[1]) + (xn[2] * xn[2] + xn[3] * xn[3]); const f32x4 t = xn * Gv[bj][n];
;                             w[n].x = cvt_pk_bf16(t[0], t[1]); w[n].y = cvt_pk_bf16(t[2], t[3]); } }
;                     if (XG) {
;                         const bool odd = (fq & 1) != 0; const u32x2 snd = odd ? w[0] : w[1]; u32x2 rcv; rcv.x = __shfl_xor(snd.x, 16); rcv.y = __shfl_xor(snd.y, 16);
;                         u32x4 o4; if (odd) { o4.x = rcv.x; o4.y = rcv.y; o4.z = w[1].x; o4.w = w[1].y; } else { o4.x = w[0].x; o4.y = w[0].y; o4.z = rcv.x; o4.w = rcv.y; }
;                         *(u32x4*)(XG + off + bj * HALF + (odd ? 12 : 0)) = o4; } }
;                 if (XG) { s += __shfl_xor(s, 16); s += __shfl_xor(s, 32); if (fq == 0) atomicAdd(ssq + row, s); } }
.LBB0_71:
	s_ashr_i32 s45, s44, 31
	s_lshl_b64 s[44:45], s[44:45], 8
	s_add_u32 s35, s44, s64
	s_addc_u32 s39, s45, s68
	v_and_or_b32 v174, v185, 15, s35
	v_mov_b32_e32 v175, s39
	s_and_b64 vcc, exec, s[42:43]
	s_cbranch_vccnz .Lepi_out_orig
	v_lshlrev_b32_e32 v164, 2, v164
	v_lshl_add_u32 v164, v174, 12, v164
	v_bfe_u32 v0, v185, 4, 1
	v_lshrrev_b32_e32 v165, 1, v164
	v_mad_u32_u24 v165, v0, 24, v165
	v_mov_b32_e32 v175, v164
	v_mov_b32_e32 v2, 0
	v_mov_b32_e32 v3, 0
	global_load_dwordx4 v[184:187], v175, s[2:3] offset:0
	global_load_dwordx4 v[188:191], v175, s[2:3] offset:64
	global_load_dwordx4 v[192:195], v175, s[2:3] offset:512
	global_load_dwordx4 v[196:199], v175, s[2:3] offset:576
	v_add_u32_e32 v175, 0x10000, v175
	global_load_dwordx4 v[200:203], v175, s[2:3] offset:0
	global_load_dwordx4 v[204:207], v175, s[2:3] offset:64
	global_load_dwordx4 v[236:239], v175, s[2:3] offset:512
	global_load_dwordx4 v[240:243], v175, s[2:3] offset:576
	v_add_u32_e32 v175, 0x10000, v175
	global_load_dwordx4 v[244:247], v175, s[2:3] offset:0
	global_load_dwordx4 v[248:251], v175, s[2:3] offset:64
	global_load_dwordx4 v[208:211], v175, s[2:3] offset:512
	global_load_dwordx4 v[212:215], v175, s[2:3] offset:576
	v_add_u32_e32 v175, 0x10000, v175
	s_waitcnt vmcnt(10)
	v_pk_fma_f32 v[184:185], v[144:145], v[52:53], v[184:185]
	v_pk_fma_f32 v[186:187], v[146:147], v[54:55], v[186:187]
	v_pk_fma_f32 v[188:189], v[140:141], v[56:57], v[188:189]
	v_pk_fma_f32 v[190:191], v[142:143], v[58:59], v[190:191]
	global_store_dwordx4 v164, v[184:187], s[6:7] offset:0
	global_store_dwordx4 v164, v[188:191], s[6:7] offset:64
	global_load_dwordx4 v[144:147], v175, s[2:3] offset:0
	global_load_dwordx4 v[140:143], v175, s[2:3] offset:64
	v_pk_fma_f32 v[2:3], v[184:185], v[184:185], v[2:3]
	v_pk_fma_f32 v[2:3], v[186:187], v[186:187], v[2:3]
	v_pk_fma_f32 v[2:3], v[188:189], v[188:189], v[2:3]
	v_pk_fma_f32 v[2:3], v[190:191], v[190:191], v[2:3]
	v_pk_mul_f32 v[252:253], v[184:185], v[170:171]
	v_cvt_pk_bf16_f32 v176, v252, v253
	v_pk_mul_f32 v[252:253], v[186:187], v[172:173]
	v_cvt_pk_bf16_f32 v177, v252, v253
	v_pk_mul_f32 v[252:253], v[188:189], v[166:167]
	v_cvt_pk_bf16_f32 v178, v252, v253
	v_pk_mul_f32 v[252:253], v[190:191], v[168:169]
	v_cvt_pk_bf16_f32 v179, v252, v253
	s_nop 1
	v_permlane16_swap_b32_e32 v176, v178
	v_permlane16_swap_b32_e32 v177, v179
	global_store_dwordx4 v165, v[176:179], s[10:11] offset:0
	s_waitcnt vmcnt(13)
	v_pk_fma_f32 v[192:193], v[136:137], v[48:49], v[192:193]
	v_pk_fma_f32 v[194:195], v[138:139], v[50:51], v[194:195]
	v_pk_fma_f32 v[196:197], v[132:133], v[44:45], v[196:197]
	v_pk_fma_f32 v[198:199], v[134:135], v[46:47], v[198:199]
	global_store_dwordx4 v164, v[192:195], s[6:7] offset:512
	global_store_dwordx4 v164, v[196:199], s[6:7] offset:576
	global_load_dwordx4 v[136:139], v175, s[2:3] offset:512
	global_load_dwordx4 v[132:135], v175, s[2:3] offset:576
	v_add_u32_e32 v175, 0x50000, v175
	v_pk_fma_f32 v[2:3], v[192:193], v[192:193], v[2:3]
	v_pk_fma_f32 v[2:3], v[194:195], v[194:195], v[2:3]
	v_pk_fma_f32 v[2:3], v[196:197], v[196:197], v[2:3]
	v_pk_fma_f32 v[2:3], v[198:199], v[198:199], v[2:3]
	v_pk_mul_f32 v[252:253], v[192:193], v[160:161]
	v_cvt_pk_bf16_f32 v176, v252, v253
	v_pk_mul_f32 v[252:253], v[194:195], v[162:163]
	v_cvt_pk_bf16_f32 v177, v252, v253
	v_pk_mul_f32 v[252:253], v[196:197], v[156:157]
	v_cvt_pk_bf16_f32 v178, v252, v253
	v_pk_mul_f32 v[252:253], v[198:199], v[158:159]
	v_cvt_pk_bf16_f32 v179, v252, v253
	s_nop 1
	v_permlane16_swap_b32_e32 v176, v178
	v_permlane16_swap_b32_e32 v177, v179
	global_store_dwordx4 v165, v[176:179], s[10:11] offset:256
	v_add_f32_e32 v2, v2, v3
	v_mov_b32_e32 v0, v2
	s_nop 1
	v_permlane16_swap_b32_e32 v2, v0
	v_add_f32_e32 v2, v2, v0
	v_mov_b32_e32 v0, v2
	s_nop 1
	v_permlane32_swap_b32_e32 v2, v0
	v_add_f32_e32 v2, v2, v0
	v_lshrrev_b32_e32 v252, 12, v164
	v_lshlrev_b32_e32 v252, 2, v252
	s_mov_b64 exec, 0xffff
	global_atomic_add_f32 v252, v2, s[14:15]
	s_mov_b64 exec, -1
	v_add_u32_e32 v164, 0x10000, v164
	v_add_u32_e32 v165, 0x8000, v165
	v_mov_b32_e32 v2, 0
	v_mov_b32_e32 v3, 0
	s_waitcnt vmcnt(17)
	v_pk_fma_f32 v[200:201], v[128:129], v[52:53], v[200:201]
	v_pk_fma_f32 v[202:203], v[130:131], v[54:55], v[202:203]
	v_pk_fma_f32 v[204:205], v[124:125], v[56:57], v[204:205]
	v_pk_fma_f32 v[206:207], v[126:127], v[58:59], v[206:207]
	global_store_dwordx4 v164, v[200:203], s[6:7] offset:0
	global_store_dwordx4 v164, v[204:207], s[6:7] offset:64
	global_load_dwordx4 v[128:131], v175, s[2:3] offset:0
	global_load_dwordx4 v[124:127], v175, s[2:3] offset:64
	v_pk_fma_f32 v[2:3], v[200:201], v[200:201], v[2:3]
	v_pk_fma_f32 v[2:3], v[202:203], v[202:203], v[2:3]
	v_pk_fma_f32 v[2:3], v[204:205], v[204:205], v[2:3]
	v_pk_fma_f32 v[2:3], v[206:207], v[206:207], v[2:3]
	v_pk_mul_f32 v[252:253], v[200:201], v[170:171]
	v_cvt_pk_bf16_f32 v176, v252, v253
	v_pk_mul_f32 v[252:253], v[202:203], v[172:173]
	v_cvt_pk_bf16_f32 v177, v252, v253
	v_pk_mul_f32 v[252:253], v[204:205], v[166:167]
	v_cvt_pk_bf16_f32 v178, v252, v253
	v_pk_mul_f32 v[252:253], v[206:207], v[168:169]
	v_cvt_pk_bf16_f32 v179, v252, v253
	s_nop 1
	v_permlane16_swap_b32_e32 v176, v178
	v_permlane16_swap_b32_e32 v177, v179
	global_store_dwordx4 v165, v[176:179], s[10:11] offset:0
	s_waitcnt vmcnt(20)
; __device__ __forceinline__ unsigned cvt_pk_bf16(float lo, float hi) { unsigned r; asm volatile("v_cvt_pk_bf16_f32 %0, %1, %2" : "=v"(r) : "v"(lo), "v"(hi)); return r; }
;     __device__ __forceinline__ void operator()(const f32x4 (&acc)[2][2][4][2], const Unit& u, int wr, int wc, int fr, int fq) const {
;     ...
;         for (int ai = 0; ai < 2; ++ai)
; #pragma unroll
;             for (int m = 0; m < 4; ++m) { const size_t row = rowb + ai * HALF + m * 16; const size_t off = row * 1024 + col0; float s = 0.f;
; #pragma unroll
;                 for (int bj = 0; bj < 2; ++bj) { u32x2 w[2];
; #pragma unroll
;                     for (int n = 0; n < 2; ++n) { const f32x4 xv = *(const __attribute__((address_space(1))) f32x4*)(xin + off + bj * HALF + n * 16);
;                         const f32x4 xn = xv + gv[bj][n] * acc[ai][bj][m][n];
;                         *(__attribute__((address_space(1))) f32x4*)(out + off + bj * HALF + n * 16) = xn;
;                         if (XG) { s += (xn[0] * xn[0] + xn[1] * xn[1]) + (xn[2] * xn[2] + xn[3] * xn[3]); const f32x4 t = xn * Gv[bj][n];
;                             w[n].x = cvt_pk_bf16(t[0], t[1]); w[n].y = cvt_pk_bf16(t[2], t[3]); } }
;                     if (XG) {
;                         const bool odd = (fq & 1) != 0; const u32x2 snd = odd ? w[0] : w[1]; u32x2 rcv; rcv.x = __shfl_xor(snd.x, 16); rcv.y = __shfl_xor(snd.y, 16);
;                         u32x4 o4; if (odd) { o4.x = rcv.x; o4.y = rcv.y; o4.z = w[1].x; o4.w = w[1].y; } else { o4.x = w[0].x; o4.y = w[0].y; o4.z = rcv.x; o4.w = rcv.y; }
;                         *(u32x4*)(XG + off + bj * HALF + (odd ? 12 : 0)) = o4; } }
;                 if (XG) { s += __shfl_xor(s, 16); s += __shfl_xor(s, 32); if (fq == 0) atomicAdd(ssq + row, s); } }
	v_pk_fma_f32 v[236:237], v[120:121], v[48:49], v[236:237]
	v_pk_fma_f32 v[238:239], v[122:123], v[50:51], v[238:239]
	v_pk_fma_f32 v[240:241], v[116:117], v[44:45], v[240:241]
	v_pk_fma_f32 v[242:243], v[118:119], v[46:47], v[242:243]
	global_store_dwordx4 v164, v[236:239], s[6:7] offset:512
	global_store_dwordx4 v164, v[240:243], s[6:7] offset:576
	global_load_dwordx4 v[120:123], v175, s[2:3] offset:512
	global_load_dwordx4 v[116:119], v175, s[2:3] offset:576
	v_add_u32_e32 v175, 0x10000, v175
	v_pk_fma_f32 v[2:3], v[236:237], v[236:237], v[2:3]
	v_pk_fma_f32 v[2:3], v[238:239], v[238:239], v[2:3]
	v_pk_fma_f32 v[2:3], v[240:241], v[240:241], v[2:3]
	v_pk_fma_f32 v[2:3], v[242:243], v[242:243], v[2:3]
	v_pk_mul_f32 v[252:253], v[236:237], v[160:161]
	v_cvt_pk_bf16_f32 v176, v252, v253
	v_pk_mul_f32 v[252:253], v[238:239], v[162:163]
	v_cvt_pk_bf16_f32 v177, v252, v253
	v_pk_mul_f32 v[252:253], v[240:241], v[156:157]
	v_cvt_pk_bf16_f32 v178, v252, v253
	v_pk_mul_f32 v[252:253], v[242:243], v[158:159]
	v_cvt_pk_bf16_f32 v179, v252, v253
	s_nop 1
	v_permlane16_swap_b32_e32 v176, v178
	v_permlane16_swap_b32_e32 v177, v179
	global_store_dwordx4 v165, v[176:179], s[10:11] offset:256
	v_add_f32_e32 v2, v2, v3
	v_mov_b32_e32 v0, v2
	s_nop 1
	v_permlane16_swap_b32_e32 v2, v0
	v_add_f32_e32 v2, v2, v0
	v_mov_b32_e32 v0, v2
	s_nop 1
	v_permlane32_swap_b32_e32 v2, v0
	v_add_f32_e32 v2, v2, v0
	v_lshrrev_b32_e32 v252, 12, v164
	v_lshlrev_b32_e32 v252, 2, v252
	s_mov_b64 exec, 0xffff
	global_atomic_add_f32 v252, v2, s[14:15]
	s_mov_b64 exec, -1
	v_add_u32_e32 v164, 0x10000, v164
	v_add_u32_e32 v165, 0x8000, v165
	v_mov_b32_e32 v2, 0
	v_mov_b32_e32 v3, 0
	s_waitcnt vmcnt(24)
	v_pk_fma_f32 v[244:245], v[112:113], v[52:53], v[244:245]
	v_pk_fma_f32 v[246:247], v[114:115], v[54:55], v[246:247]
	v_pk_fma_f32 v[248:249], v[108:109], v[56:57], v[248:249]
	v_pk_fma_f32 v[250:251], v[110:111], v[58:59], v[250:251]
	global_store_dwordx4 v164, v[244:247], s[6:7] offset:0
	global_store_dwordx4 v164, v[248:251], s[6:7] offset:64
	global_load_dwordx4 v[112:115], v175, s[2:3] offset:0
	global_load_dwordx4 v[108:111], v175, s[2:3] offset:64
	v_pk_fma_f32 v[2:3], v[244:245], v[244:245], v[2:3]
	v_pk_fma_f32 v[2:3], v[246:247], v[246:247], v[2:3]
	v_pk_fma_f32 v[2:3], v[248:249], v[248:249], v[2:3]
	v_pk_fma_f32 v[2:3], v[250:251], v[250:251], v[2:3]
	v_pk_mul_f32 v[252:253], v[244:245], v[170:171]
	v_cvt_pk_bf16_f32 v176, v252, v253
	v_pk_mul_f32 v[252:253], v[246:247], v[172:173]
	v_cvt_pk_bf16_f32 v177, v252, v253
	v_pk_mul_f32 v[252:253], v[248:249], v[166:167]
	v_cvt_pk_bf16_f32 v178, v252, v253
	v_pk_mul_f32 v[252:253], v[250:251], v[168:169]
	v_cvt_pk_bf16_f32 v179, v252, v253
	s_nop 1
	v_permlane16_swap_b32_e32 v176, v178
	v_permlane16_swap_b32_e32 v177, v179
	global_store_dwordx4 v165, v[176:179], s[10:11] offset:0
	s_waitcnt vmcnt(27)
	v_pk_fma_f32 v[208:209], v[104:105], v[48:49], v[208:209]
	v_pk_fma_f32 v[210:211], v[106:107], v[50:51], v[210:211]
	v_pk_fma_f32 v[212:213], v[100:101], v[44:45], v[212:213]
	v_pk_fma_f32 v[214:215], v[102:103], v[46:47], v[214:215]
	global_store_dwordx4 v164, v[208:211], s[6:7] offset:512
	global_store_dwordx4 v164, v[212:215], s[6:7] offset:576
	global_load_dwordx4 v[104:107], v175, s[2:3] offset:512
	global_load_dwordx4 v[100:103], v175, s[2:3] offset:576
	v_add_u32_e32 v175, 0x10000, v175
	v_pk_fma_f32 v[2:3], v[208:209], v[208:209], v[2:3]
	v_pk_fma_f32 v[2:3], v[210:211], v[210:211], v[2:3]
	v_pk_fma_f32 v[2:3], v[212:213], v[212:213], v[2:3]
	v_pk_fma_f32 v[2:3], v[214:215], v[214:215], v[2:3]
	v_pk_mul_f32 v[252:253], v[208:209], v[160:161]
	v_cvt_pk_bf16_f32 v176, v252, v253
	v_pk_mul_f32 v[252:253], v[210:211], v[162:163]
	v_cvt_pk_bf16_f32 v177, v252, v253
	v_pk_mul_f32 v[252:253], v[212:213], v[156:157]
	v_cvt_pk_bf16_f32 v178, v252, v253
	v_pk_mul_f32 v[252:253], v[214:215], v[158:159]
	v_cvt_pk_bf16_f32 v179, v252, v253
	s_nop 1
	v_permlane16_swap_b32_e32 v176, v178
	v_permlane16_swap_b32_e32 v177, v179
	global_store_dwordx4 v165, v[176:179], s[10:11] offset:256
	v_add_f32_e32 v2, v2, v3
	v_mov_b32_e32 v0, v2
	s_nop 1
	v_permlane16_swap_b32_e32 v2, v0
	v_add_f32_e32 v2, v2, v0
	v_mov_b32_e32 v0, v2
	s_nop 1
	v_permlane32_swap_b32_e32 v2, v0
	v_add_f32_e32 v2, v2, v0
	v_lshrrev_b32_e32 v252, 12, v164
	v_lshlrev_b32_e32 v252, 2, v252
	s_mov_b64 exec, 0xffff
	global_atomic_add_f32 v252, v2, s[14:15]
	s_mov_b64 exec, -1
	v_add_u32_e32 v164, 0x10000, v164
	v_add_u32_e32 v165, 0x8000, v165
	v_mov_b32_e32 v2, 0
	v_mov_b32_e32 v3, 0
	s_waitcnt vmcnt(29)
	v_pk_fma_f32 v[144:145], v[96:97], v[52:53], v[144:145]
	v_pk_fma_f32 v[146:147], v[98:99], v[54:55], v[146:147]
	v_pk_fma_f32 v[140:141], v[92:93], v[56:57], v[140:141]
	v_pk_fma_f32 v[142:143], v[94:95], v[58:59], v[142:143]
	global_store_dwordx4 v164, v[144:147], s[6:7] offset:0
	global_store_dwordx4 v164, v[140:143], s[6:7] offset:64
	global_load_dwordx4 v[96:99], v175, s[2:3] offset:0
	global_load_dwordx4 v[92:95], v175, s[2:3] offset:64
	v_pk_fma_f32 v[2:3], v[144:145], v[144:145], v[2:3]
	v_pk_fma_f32 v[2:3], v[146:147], v[146:147], v[2:3]
	v_pk_fma_f32 v[2:3], v[140:141], v[140:141], v[2:3]
	v_pk_fma_f32 v[2:3], v[142:143], v[142:143], v[2:3]
	v_pk_mul_f32 v[252:253], v[144:145], v[170:171]
	v_cvt_pk_bf16_f32 v176, v252, v253
	v_pk_mul_f32 v[252:253], v[146:147], v[172:173]
	v_cvt_pk_bf16_f32 v177, v252, v253
	v_pk_mul_f32 v[252:253], v[140:141], v[166:167]
	v_cvt_pk_bf16_f32 v178, v252, v253
	v_pk_mul_f32 v[252:253], v[142:143], v[168:169]
	v_cvt_pk_bf16_f32 v179, v252, v253
	s_nop 1
	v_permlane16_swap_b32_e32 v176, v178
	v_permlane16_swap_b32_e32 v177, v179
	global_store_dwordx4 v165, v[176:179], s[10:11] offset:0
	s_waitcnt vmcnt(29)
; __device__ __forceinline__ unsigned cvt_pk_bf16(float lo, float hi) { unsigned r; asm volatile("v_cvt_pk_bf16_f32 %0, %1, %2" : "=v"(r) : "v"(lo), "v"(hi)); return r; }
;     __device__ __forceinline__ void operator()(const f32x4 (&acc)[2][2][4][2], const Unit& u, int wr, int wc, int fr, int fq) const {
;     ...
;             for (int m = 0; m < 4; ++m) { const size_t row = rowb + ai * HALF + m * 16; const size_t off = row * 1024 + col0; float s = 0.f;
; #pragma unroll
;                 for (int bj = 0; bj < 2; ++bj) { u32x2 w[2];
; #pragma unroll
;                     for (int n = 0; n < 2; ++n) { const f32x4 xv = *(const __attribute__((address_space(1))) f32x4*)(xin + off + bj * HALF + n * 16);
;                         const f32x4 xn = xv + gv[bj][n] * acc[ai][bj][m][n];
;                         *(__attribute__((address_space(1))) f32x4*)(out + off + bj * HALF + n * 16) = xn;
;                         if (XG) { s += (xn[0] * xn[0] + xn[1] * xn[1]) + (xn[2] * xn[2] + xn[3] * xn[3]); const f32x4 t = xn * Gv[bj][n];
;                             w[n].x = cvt_pk_bf16(t[0], t[1]); w[n].y = cvt_pk_bf16(t[2], t[3]); } }
;                     if (XG) {
;                         const bool odd = (fq & 1) != 0; const u32x2 snd = odd ? w[0] : w[1]; u32x2 rcv; rcv.x = __shfl_xor(snd.x, 16); rcv.y = __shfl_xor(snd.y, 16);
;                         u32x4 o4; if (odd) { o4.x = rcv.x; o4.y = rcv.y; o4.z = w[1].x; o4.w = w[1].y; } else { o4.x = w[0].x; o4.y = w[0].y; o4.z = rcv.x; o4.w = rcv.y; }
;                         *(u32x4*)(XG + off + bj * HALF + (odd ? 12 : 0)) = o4; } }
;                 if (XG) { s += __shfl_xor(s, 16); s += __shfl_xor(s, 32); if (fq == 0) atomicAdd(ssq + row, s); } }
	v_pk_fma_f32 v[136:137], v[88:89], v[48:49], v[136:137]
	v_pk_fma_f32 v[138:139], v[90:91], v[50:51], v[138:139]
	v_pk_fma_f32 v[132:133], v[84:85], v[44:45], v[132:133]
	v_pk_fma_f32 v[134:135], v[86:87], v[46:47], v[134:135]
	global_store_dwordx4 v164, v[136:139], s[6:7] offset:512
	global_store_dwordx4 v164, v[132:135], s[6:7] offset:576
	global_load_dwordx4 v[88:91], v175, s[2:3] offset:512
	global_load_dwordx4 v[84:87], v175, s[2:3] offset:576
	v_add_u32_e32 v175, 0x10000, v175
	v_pk_fma_f32 v[2:3], v[136:137], v[136:137], v[2:3]
	v_pk_fma_f32 v[2:3], v[138:139], v[138:139], v[2:3]
	v_pk_fma_f32 v[2:3], v[132:133], v[132:133], v[2:3]
	v_pk_fma_f32 v[2:3], v[134:135], v[134:135], v[2:3]
	v_pk_mul_f32 v[252:253], v[136:137], v[160:161]
	v_cvt_pk_bf16_f32 v176, v252, v253
	v_pk_mul_f32 v[252:253], v[138:139], v[162:163]
	v_cvt_pk_bf16_f32 v177, v252, v253
	v_pk_mul_f32 v[252:253], v[132:133], v[156:157]
	v_cvt_pk_bf16_f32 v178, v252, v253
	v_pk_mul_f32 v[252:253], v[134:135], v[158:159]
	v_cvt_pk_bf16_f32 v179, v252, v253
	s_nop 1
	v_permlane16_swap_b32_e32 v176, v178
	v_permlane16_swap_b32_e32 v177, v179
	global_store_dwordx4 v165, v[176:179], s[10:11] offset:256
	v_add_f32_e32 v2, v2, v3
	v_mov_b32_e32 v0, v2
	s_nop 1
	v_permlane16_swap_b32_e32 v2, v0
	v_add_f32_e32 v2, v2, v0
	v_mov_b32_e32 v0, v2
	s_nop 1
	v_permlane32_swap_b32_e32 v2, v0
	v_add_f32_e32 v2, v2, v0
	v_lshrrev_b32_e32 v252, 12, v164
	v_lshlrev_b32_e32 v252, 2, v252
	s_mov_b64 exec, 0xffff
	global_atomic_add_f32 v252, v2, s[14:15]
	s_mov_b64 exec, -1
	v_add_u32_e32 v164, 0x50000, v164
	v_add_u32_e32 v165, 0x28000, v165
	v_mov_b32_e32 v2, 0
	v_mov_b32_e32 v3, 0
	s_waitcnt vmcnt(29)
	v_pk_fma_f32 v[128:129], v[80:81], v[52:53], v[128:129]
	v_pk_fma_f32 v[130:131], v[82:83], v[54:55], v[130:131]
	v_pk_fma_f32 v[124:125], v[76:77], v[56:57], v[124:125]
	v_pk_fma_f32 v[126:127], v[78:79], v[58:59], v[126:127]
	global_store_dwordx4 v164, v[128:131], s[6:7] offset:0
	global_store_dwordx4 v164, v[124:127], s[6:7] offset:64
	global_load_dwordx4 v[80:83], v175, s[2:3] offset:0
	global_load_dwordx4 v[76:79], v175, s[2:3] offset:64
	v_pk_fma_f32 v[2:3], v[128:129], v[128:129], v[2:3]
	v_pk_fma_f32 v[2:3], v[130:131], v[130:131], v[2:3]
	v_pk_fma_f32 v[2:3], v[124:125], v[124:125], v[2:3]
	v_pk_fma_f32 v[2:3], v[126:127], v[126:127], v[2:3]
	v_pk_mul_f32 v[252:253], v[128:129], v[170:171]
	v_cvt_pk_bf16_f32 v176, v252, v253
	v_pk_mul_f32 v[252:253], v[130:131], v[172:173]
	v_cvt_pk_bf16_f32 v177, v252, v253
	v_pk_mul_f32 v[252:253], v[124:125], v[166:167]
	v_cvt_pk_bf16_f32 v178, v252, v253
	v_pk_mul_f32 v[252:253], v[126:127], v[168:169]
	v_cvt_pk_bf16_f32 v179, v252, v253
	s_nop 1
	v_permlane16_swap_b32_e32 v176, v178
	v_permlane16_swap_b32_e32 v177, v179
	global_store_dwordx4 v165, v[176:179], s[10:11] offset:0
	s_waitcnt vmcnt(29)
	v_pk_fma_f32 v[120:121], v[72:73], v[48:49], v[120:121]
	v_pk_fma_f32 v[122:123], v[74:75], v[50:51], v[122:123]
	v_pk_fma_f32 v[116:117], v[68:69], v[44:45], v[116:117]
	v_pk_fma_f32 v[118:119], v[70:71], v[46:47], v[118:119]
	global_store_dwordx4 v164, v[120:123], s[6:7] offset:512
	global_store_dwordx4 v164, v[116:119], s[6:7] offset:576
	global_load_dwordx4 v[72:75], v175, s[2:3] offset:512
	global_load_dwordx4 v[68:71], v175, s[2:3] offset:576
	v_pk_fma_f32 v[2:3], v[120:121], v[120:121], v[2:3]
	v_pk_fma_f32 v[2:3], v[122:123], v[122:123], v[2:3]
	v_pk_fma_f32 v[2:3], v[116:117], v[116:117], v[2:3]
	v_pk_fma_f32 v[2:3], v[118:119], v[118:119], v[2:3]
	v_pk_mul_f32 v[252:253], v[120:121], v[160:161]
	v_cvt_pk_bf16_f32 v176, v252, v253
	v_pk_mul_f32 v[252:253], v[122:123], v[162:163]
	v_cvt_pk_bf16_f32 v177, v252, v253
	v_pk_mul_f32 v[252:253], v[116:117], v[156:157]
	v_cvt_pk_bf16_f32 v178, v252, v253
	v_pk_mul_f32 v[252:253], v[118:119], v[158:159]
	v_cvt_pk_bf16_f32 v179, v252, v253
	s_nop 1
	v_permlane16_swap_b32_e32 v176, v178
	v_permlane16_swap_b32_e32 v177, v179
	global_store_dwordx4 v165, v[176:179], s[10:11] offset:256
	v_add_f32_e32 v2, v2, v3
	v_mov_b32_e32 v0, v2
	s_nop 1
	v_permlane16_swap_b32_e32 v2, v0
	v_add_f32_e32 v2, v2, v0
	v_mov_b32_e32 v0, v2
	s_nop 1
	v_permlane32_swap_b32_e32 v2, v0
	v_add_f32_e32 v2, v2, v0
	v_lshrrev_b32_e32 v252, 12, v164
	v_lshlrev_b32_e32 v252, 2, v252
	s_mov_b64 exec, 0xffff
	global_atomic_add_f32 v252, v2, s[14:15]
	s_mov_b64 exec, -1
	v_add_u32_e32 v164, 0x10000, v164
	v_add_u32_e32 v165, 0x8000, v165
	v_mov_b32_e32 v2, 0
	v_mov_b32_e32 v3, 0
	s_waitcnt vmcnt(29)
	v_pk_fma_f32 v[112:113], v[64:65], v[52:53], v[112:113]
	v_pk_fma_f32 v[114:115], v[66:67], v[54:55], v[114:115]
	v_pk_fma_f32 v[108:109], v[60:61], v[56:57], v[108:109]
	v_pk_fma_f32 v[110:111], v[62:63], v[58:59], v[110:111]
	global_store_dwordx4 v164, v[112:115], s[6:7] offset:0
	global_store_dwordx4 v164, v[108:111], s[6:7] offset:64
	v_pk_fma_f32 v[2:3], v[112:113], v[112:113], v[2:3]
	v_pk_fma_f32 v[2:3], v[114:115], v[114:115], v[2:3]
	v_pk_fma_f32 v[2:3], v[108:109], v[108:109], v[2:3]
	v_pk_fma_f32 v[2:3], v[110:111], v[110:111], v[2:3]
	v_pk_mul_f32 v[252:253], v[112:113], v[170:171]
	v_cvt_pk_bf16_f32 v176, v252, v253
	v_pk_mul_f32 v[252:253], v[114:115], v[172:173]
	v_cvt_pk_bf16_f32 v177, v252, v253
	v_pk_mul_f32 v[252:253], v[108:109], v[166:167]
	v_cvt_pk_bf16_f32 v178, v252, v253
	v_pk_mul_f32 v[252:253], v[110:111], v[168:169]
	v_cvt_pk_bf16_f32 v179, v252, v253
	s_nop 1
	v_permlane16_swap_b32_e32 v176, v178
	v_permlane16_swap_b32_e32 v177, v179
	global_store_dwordx4 v165, v[176:179], s[10:11] offset:0
	s_waitcnt vmcnt(27)
; __device__ __forceinline__ unsigned cvt_pk_bf16(float lo, float hi) { unsigned r; asm volatile("v_cvt_pk_bf16_f32 %0, %1, %2" : "=v"(r) : "v"(lo), "v"(hi)); return r; }
;     __device__ __forceinline__ void operator()(const f32x4 (&acc)[2][2][4][2], const Unit& u, int wr, int wc, int fr, int fq) const {
;     ...
;             for (int m = 0; m < 4; ++m) { const size_t row = rowb + ai * HALF + m * 16; const size_t off = row * 1024 + col0; float s = 0.f;
; #pragma unroll
;                 for (int bj = 0; bj < 2; ++bj) { u32x2 w[2];
; #pragma unroll
;                     for (int n = 0; n < 2; ++n) { const f32x4 xv = *(const __attribute__((address_space(1))) f32x4*)(xin + off + bj * HALF + n * 16);
;                         const f32x4 xn = xv + gv[bj][n] * acc[ai][bj][m][n];
;                         *(__attribute__((address_space(1))) f32x4*)(out + off + bj * HALF + n * 16) = xn;
;                         if (XG) { s += (xn[0] * xn[0] + xn[1] * xn[1]) + (xn[2] * xn[2] + xn[3] * xn[3]); const f32x4 t = xn * Gv[bj][n];
;                             w[n].x = cvt_pk_bf16(t[0], t[1]); w[n].y = cvt_pk_bf16(t[2], t[3]); } }
;                     if (XG) {
;                         const bool odd = (fq & 1) != 0; const u32x2 snd = odd ? w[0] : w[1]; u32x2 rcv; rcv.x = __shfl_xor(snd.x, 16); rcv.y = __shfl_xor(snd.y, 16);
;                         u32x4 o4; if (odd) { o4.x = rcv.x; o4.y = rcv.y; o4.z = w[1].x; o4.w = w[1].y; } else { o4.x = w[0].x; o4.y = w[0].y; o4.z = rcv.x; o4.w = rcv.y; }
;                         *(u32x4*)(XG + off + bj * HALF + (odd ? 12 : 0)) = o4; } }
;                 if (XG) { s += __shfl_xor(s, 16); s += __shfl_xor(s, 32); if (fq == 0) atomicAdd(ssq + row, s); } }
	v_pk_fma_f32 v[104:105], v[40:41], v[48:49], v[104:105]
	v_pk_fma_f32 v[106:107], v[42:43], v[50:51], v[106:107]
	v_pk_fma_f32 v[100:101], v[36:37], v[44:45], v[100:101]
	v_pk_fma_f32 v[102:103], v[38:39], v[46:47], v[102:103]
	global_store_dwordx4 v164, v[104:107], s[6:7] offset:512
	global_store_dwordx4 v164, v[100:103], s[6:7] offset:576
	v_pk_fma_f32 v[2:3], v[104:105], v[104:105], v[2:3]
	v_pk_fma_f32 v[2:3], v[106:107], v[106:107], v[2:3]
	v_pk_fma_f32 v[2:3], v[100:101], v[100:101], v[2:3]
	v_pk_fma_f32 v[2:3], v[102:103], v[102:103], v[2:3]
	v_pk_mul_f32 v[252:253], v[104:105], v[160:161]
	v_cvt_pk_bf16_f32 v176, v252, v253
	v_pk_mul_f32 v[252:253], v[106:107], v[162:163]
	v_cvt_pk_bf16_f32 v177, v252, v253
	v_pk_mul_f32 v[252:253], v[100:101], v[156:157]
	v_cvt_pk_bf16_f32 v178, v252, v253
	v_pk_mul_f32 v[252:253], v[102:103], v[158:159]
	v_cvt_pk_bf16_f32 v179, v252, v253
	s_nop 1
	v_permlane16_swap_b32_e32 v176, v178
	v_permlane16_swap_b32_e32 v177, v179
	global_store_dwordx4 v165, v[176:179], s[10:11] offset:256
	v_add_f32_e32 v2, v2, v3
	v_mov_b32_e32 v0, v2
	s_nop 1
	v_permlane16_swap_b32_e32 v2, v0
	v_add_f32_e32 v2, v2, v0
	v_mov_b32_e32 v0, v2
	s_nop 1
	v_permlane32_swap_b32_e32 v2, v0
	v_add_f32_e32 v2, v2, v0
	v_lshrrev_b32_e32 v252, 12, v164
	v_lshlrev_b32_e32 v252, 2, v252
	s_mov_b64 exec, 0xffff
	global_atomic_add_f32 v252, v2, s[14:15]
	s_mov_b64 exec, -1
	v_add_u32_e32 v164, 0x10000, v164
	v_add_u32_e32 v165, 0x8000, v165
	v_mov_b32_e32 v2, 0
	v_mov_b32_e32 v3, 0
	s_waitcnt vmcnt(25)
	v_pk_fma_f32 v[96:97], v[32:33], v[52:53], v[96:97]
	v_pk_fma_f32 v[98:99], v[34:35], v[54:55], v[98:99]
	v_pk_fma_f32 v[92:93], v[28:29], v[56:57], v[92:93]
	v_pk_fma_f32 v[94:95], v[30:31], v[58:59], v[94:95]
	global_store_dwordx4 v164, v[96:99], s[6:7] offset:0
	global_store_dwordx4 v164, v[92:95], s[6:7] offset:64
	v_pk_fma_f32 v[2:3], v[96:97], v[96:97], v[2:3]
	v_pk_fma_f32 v[2:3], v[98:99], v[98:99], v[2:3]
	v_pk_fma_f32 v[2:3], v[92:93], v[92:93], v[2:3]
	v_pk_fma_f32 v[2:3], v[94:95], v[94:95], v[2:3]
	v_pk_mul_f32 v[252:253], v[96:97], v[170:171]
	v_cvt_pk_bf16_f32 v176, v252, v253
	v_pk_mul_f32 v[252:253], v[98:99], v[172:173]
	v_cvt_pk_bf16_f32 v177, v252, v253
	v_pk_mul_f32 v[252:253], v[92:93], v[166:167]
	v_cvt_pk_bf16_f32 v178, v252, v253
	v_pk_mul_f32 v[252:253], v[94:95], v[168:169]
	v_cvt_pk_bf16_f32 v179, v252, v253
	s_nop 1
	v_permlane16_swap_b32_e32 v176, v178
	v_permlane16_swap_b32_e32 v177, v179
	global_store_dwordx4 v165, v[176:179], s[10:11] offset:0
	s_waitcnt vmcnt(23)
	v_pk_fma_f32 v[88:89], v[24:25], v[48:49], v[88:89]
	v_pk_fma_f32 v[90:91], v[26:27], v[50:51], v[90:91]
	v_pk_fma_f32 v[84:85], v[20:21], v[44:45], v[84:85]
	v_pk_fma_f32 v[86:87], v[22:23], v[46:47], v[86:87]
	global_store_dwordx4 v164, v[88:91], s[6:7] offset:512
	global_store_dwordx4 v164, v[84:87], s[6:7] offset:576
	v_pk_fma_f32 v[2:3], v[88:89], v[88:89], v[2:3]
	v_pk_fma_f32 v[2:3], v[90:91], v[90:91], v[2:3]
	v_pk_fma_f32 v[2:3], v[84:85], v[84:85], v[2:3]
	v_pk_fma_f32 v[2:3], v[86:87], v[86:87], v[2:3]
	v_pk_mul_f32 v[252:253], v[88:89], v[160:161]
	v_cvt_pk_bf16_f32 v176, v252, v253
	v_pk_mul_f32 v[252:253], v[90:91], v[162:163]
	v_cvt_pk_bf16_f32 v177, v252, v253
	v_pk_mul_f32 v[252:253], v[84:85], v[156:157]
	v_cvt_pk_bf16_f32 v178, v252, v253
	v_pk_mul_f32 v[252:253], v[86:87], v[158:159]
	v_cvt_pk_bf16_f32 v179, v252, v253
	s_nop 1
	v_permlane16_swap_b32_e32 v176, v178
	v_permlane16_swap_b32_e32 v177, v179
	global_store_dwordx4 v165, v[176:179], s[10:11] offset:256
	v_add_f32_e32 v2, v2, v3
	v_mov_b32_e32 v0, v2
	s_nop 1
	v_permlane16_swap_b32_e32 v2, v0
	v_add_f32_e32 v2, v2, v0
	v_mov_b32_e32 v0, v2
	s_nop 1
	v_permlane32_swap_b32_e32 v2, v0
	v_add_f32_e32 v2, v2, v0
	v_lshrrev_b32_e32 v252, 12, v164
	v_lshlrev_b32_e32 v252, 2, v252
	s_mov_b64 exec, 0xffff
	global_atomic_add_f32 v252, v2, s[14:15]
	s_mov_b64 exec, -1
	v_add_u32_e32 v164, 0x10000, v164
	v_add_u32_e32 v165, 0x8000, v165
	v_mov_b32_e32 v2, 0
	v_mov_b32_e32 v3, 0
	s_waitcnt vmcnt(21)
	v_pk_fma_f32 v[80:81], v[16:17], v[52:53], v[80:81]
	v_pk_fma_f32 v[82:83], v[18:19], v[54:55], v[82:83]
	v_pk_fma_f32 v[76:77], v[12:13], v[56:57], v[76:77]
	v_pk_fma_f32 v[78:79], v[14:15], v[58:59], v[78:79]
	global_store_dwordx4 v164, v[80:83], s[6:7] offset:0
	global_store_dwordx4 v164, v[76:79], s[6:7] offset:64
	v_pk_fma_f32 v[2:3], v[80:81], v[80:81], v[2:3]
	v_pk_fma_f32 v[2:3], v[82:83], v[82:83], v[2:3]
	v_pk_fma_f32 v[2:3], v[76:77], v[76:77], v[2:3]
	v_pk_fma_f32 v[2:3], v[78:79], v[78:79], v[2:3]
	v_pk_mul_f32 v[252:253], v[80:81], v[170:171]
	v_cvt_pk_bf16_f32 v176, v252, v253
	v_pk_mul_f32 v[252:253], v[82:83], v[172:173]
	v_cvt_pk_bf16_f32 v177, v252, v253
	v_pk_mul_f32 v[252:253], v[76:77], v[166:167]
	v_cvt_pk_bf16_f32 v178, v252, v253
	v_pk_mul_f32 v[252:253], v[78:79], v[168:169]
	v_cvt_pk_bf16_f32 v179, v252, v253
	s_nop 1
	v_permlane16_swap_b32_e32 v176, v178
	v_permlane16_swap_b32_e32 v177, v179
	global_store_dwordx4 v165, v[176:179], s[10:11] offset:0
	s_waitcnt vmcnt(19)
	v_pk_fma_f32 v[72:73], v[8:9], v[48:49], v[72:73]
	v_pk_fma_f32 v[74:75], v[10:11], v[50:51], v[74:75]
	v_pk_fma_f32 v[68:69], v[4:5], v[44:45], v[68:69]
	v_pk_fma_f32 v[70:71], v[6:7], v[46:47], v[70:71]
	global_store_dwordx4 v164, v[72:75], s[6:7] offset:512
	global_store_dwordx4 v164, v[68:71], s[6:7] offset:576
	v_pk_fma_f32 v[2:3], v[72:73], v[72:73], v[2:3]
	v_pk_fma_f32 v[2:3], v[74:75], v[74:75], v[2:3]
	v_pk_fma_f32 v[2:3], v[68:69], v[68:69], v[2:3]
	v_pk_fma_f32 v[2:3], v[70:71], v[70:71], v[2:3]
	v_pk_mul_f32 v[252:253], v[72:73], v[160:161]
	v_cvt_pk_bf16_f32 v176, v252, v253
	v_pk_mul_f32 v[252:253], v[74:75], v[162:163]
	v_cvt_pk_bf16_f32 v177, v252, v253
	v_pk_mul_f32 v[252:253], v[68:69], v[156:157]
	v_cvt_pk_bf16_f32 v178, v252, v253
	v_pk_mul_f32 v[252:253], v[70:71], v[158:159]
	v_cvt_pk_bf16_f32 v179, v252, v253
	s_nop 1
	v_permlane16_swap_b32_e32 v176, v178
	v_permlane16_swap_b32_e32 v177, v179
	global_store_dwordx4 v165, v[176:179], s[10:11] offset:256
	v_add_f32_e32 v2, v2, v3
	v_mov_b32_e32 v0, v2
	s_nop 1
	v_permlane16_swap_b32_e32 v2, v0
	v_add_f32_e32 v2, v2, v0
	v_mov_b32_e32 v0, v2
	s_nop 1
	v_permlane32_swap_b32_e32 v2, v0
	v_add_f32_e32 v2, v2, v0
	v_lshrrev_b32_e32 v252, 12, v164
	v_lshlrev_b32_e32 v252, 2, v252
	s_mov_b64 exec, 0xffff
	global_atomic_add_f32 v252, v2, s[14:15]
	s_mov_b64 exec, -1
	s_branch .LBB0_188

; __device__ __forceinline__ unsigned cvt_pk_bf16(float lo, float hi) { unsigned r; asm volatile("v_cvt_pk_bf16_f32 %0, %1, %2" : "=v"(r) : "v"(lo), "v"(hi)); return r; }
;     __device__ __forceinline__ void operator()(const f32x4 (&acc)[2][2][4][2], const Unit& u, int wr, int wc, int fr, int fq) const {
;     ...
;         const size_t rowb = (size_t)u.pm * BM + wr * 64 + fr; const int col0 = u.pn * BM + wc * 32 + 4 * fq; const float* gb = gmod + (size_t)(u.pm >> 4) * 6144;
;         f32x4 gv[2][2], Gv[2][2];
; #pragma unroll
;         for (int bj = 0; bj < 2; ++bj)
; #pragma unroll
;             for (int n = 0; n < 2; ++n) { gv[bj][n] = *(const f32x4*)(gb + col0 + bj * HALF + n * 16);
;                 if (XG) Gv[bj][n] = *(const f32x4*)(gnorm + col0 + bj * HALF + n * 16) * (1.0f + *(const f32x4*)(scmod + (size_t)(u.pm >> 4) * 6144 + col0 + bj * HALF + n * 16)); }
; #pragma unroll
;         for (int ai = 0; ai < 2; ++ai)
; #pragma unroll
;             for (int m = 0; m < 4; ++m) { const size_t row = rowb + ai * HALF + m * 16; const size_t off = row * 1024 + col0; float s = 0.f;
; #pragma unroll
;                 for (int bj = 0; bj < 2; ++bj) { u32x2 w[2];
; #pragma unroll
;                     for (int n = 0; n < 2; ++n) { const f32x4 xv = *(const __attribute__((address_space(1))) f32x4*)(xin + off + bj * HALF + n * 16);
;                         const f32x4 xn = xv + gv[bj][n] * acc[ai][bj][m][n];
;                         *(__attribute__((address_space(1))) f32x4*)(out + off + bj * HALF + n * 16) = xn;
;                         if (XG) { s += (xn[0] * xn[0] + xn[1] * xn[1]) + (xn[2] * xn[2] + xn[3] * xn[3]); const f32x4 t = xn * Gv[bj][n];
;                             w[n].x = cvt_pk_bf16(t[0], t[1]); w[n].y = cvt_pk_bf16(t[2], t[3]); } }
;                     if (XG) {
;                         const bool odd = (fq & 1) != 0; const u32x2 snd = odd ? w[0] : w[1]; u32x2 rcv; rcv.x = __shfl_xor(snd.x, 16); rcv.y = __shfl_xor(snd.y, 16);
;                         u32x4 o4; if (odd) { o4.x = rcv.x; o4.y = rcv.y; o4.z = w[1].x; o4.w = w[1].y; } else { o4.x = w[0].x; o4.y = w[0].y; o4.z = rcv.x; o4.w = rcv.y; }
;                         *(u32x4*)(XG + off + bj * HALF + (odd ? 12 : 0)) = o4; } }
;                 if (XG) { s += __shfl_xor(s, 16); s += __shfl_xor(s, 32); if (fq == 0) atomicAdd(ssq + row, s); } }
.LBB0_702:
	s_ashr_i32 s19, s18, 31
	s_lshl_b64 s[18:19], s[18:19], 8
	s_add_u32 s18, s18, s61
	s_addc_u32 s19, s19, s65
	v_and_or_b32 v174, v183, 15, s18
	v_mov_b32_e32 v175, s19
	s_and_b64 vcc, exec, s[42:43]
	s_cbranch_vccnz .Lepi_ffn2_orig
	v_lshlrev_b32_e32 v164, 2, v164
	v_lshl_add_u32 v164, v174, 12, v164
	v_bfe_u32 v0, v183, 4, 1
	v_lshrrev_b32_e32 v165, 1, v164
	v_mad_u32_u24 v165, v0, 24, v165
	v_mov_b32_e32 v175, v164
	v_mov_b32_e32 v2, 0
	v_mov_b32_e32 v3, 0
	global_load_dwordx4 v[182:185], v175, s[2:3] offset:0
	global_load_dwordx4 v[186:189], v175, s[2:3] offset:64
	global_load_dwordx4 v[190:193], v175, s[2:3] offset:512
	global_load_dwordx4 v[194:197], v175, s[2:3] offset:576
	v_add_u32_e32 v175, 0x10000, v175
	global_load_dwordx4 v[198:201], v175, s[2:3] offset:0
	global_load_dwordx4 v[202:205], v175, s[2:3] offset:64
	global_load_dwordx4 v[236:239], v175, s[2:3] offset:512
	global_load_dwordx4 v[240:243], v175, s[2:3] offset:576
	v_add_u32_e32 v175, 0x10000, v175
	global_load_dwordx4 v[244:247], v175, s[2:3] offset:0
	global_load_dwordx4 v[248:251], v175, s[2:3] offset:64
	global_load_dwordx4 v[206:209], v175, s[2:3] offset:512
	global_load_dwordx4 v[210:213], v175, s[2:3] offset:576
	v_add_u32_e32 v175, 0x10000, v175
	s_waitcnt vmcnt(10)
	v_pk_fma_f32 v[182:183], v[64:65], v[72:73], v[182:183]
	v_pk_fma_f32 v[184:185], v[66:67], v[74:75], v[184:185]
	v_pk_fma_f32 v[186:187], v[144:145], v[76:77], v[186:187]
	v_pk_fma_f32 v[188:189], v[146:147], v[78:79], v[188:189]
	global_store_dwordx4 v164, v[182:185], s[2:3] offset:0
	global_store_dwordx4 v164, v[186:189], s[2:3] offset:64
	global_load_dwordx4 v[64:67], v175, s[2:3] offset:0
	global_load_dwordx4 v[144:147], v175, s[2:3] offset:64
	v_pk_fma_f32 v[2:3], v[182:183], v[182:183], v[2:3]
	v_pk_fma_f32 v[2:3], v[184:185], v[184:185], v[2:3]
	v_pk_fma_f32 v[2:3], v[186:187], v[186:187], v[2:3]
	v_pk_fma_f32 v[2:3], v[188:189], v[188:189], v[2:3]
	v_pk_mul_f32 v[252:253], v[182:183], v[170:171]
	v_cvt_pk_bf16_f32 v176, v252, v253
	v_pk_mul_f32 v[252:253], v[184:185], v[172:173]
	v_cvt_pk_bf16_f32 v177, v252, v253
	v_pk_mul_f32 v[252:253], v[186:187], v[166:167]
	v_cvt_pk_bf16_f32 v178, v252, v253
	v_pk_mul_f32 v[252:253], v[188:189], v[168:169]
	v_cvt_pk_bf16_f32 v179, v252, v253
	s_nop 1
	v_permlane16_swap_b32_e32 v176, v178
	v_permlane16_swap_b32_e32 v177, v179
	global_store_dwordx4 v165, v[176:179], s[92:93] offset:0
	s_waitcnt vmcnt(13)
	v_pk_fma_f32 v[190:191], v[140:141], v[60:61], v[190:191]
	v_pk_fma_f32 v[192:193], v[142:143], v[62:63], v[192:193]
	v_pk_fma_f32 v[194:195], v[136:137], v[56:57], v[194:195]
	v_pk_fma_f32 v[196:197], v[138:139], v[58:59], v[196:197]
	global_store_dwordx4 v164, v[190:193], s[2:3] offset:512
	global_store_dwordx4 v164, v[194:197], s[2:3] offset:576
	global_load_dwordx4 v[140:143], v175, s[2:3] offset:512
	global_load_dwordx4 v[136:139], v175, s[2:3] offset:576
	v_add_u32_e32 v175, 0x50000, v175
	v_pk_fma_f32 v[2:3], v[190:191], v[190:191], v[2:3]
	v_pk_fma_f32 v[2:3], v[192:193], v[192:193], v[2:3]
	v_pk_fma_f32 v[2:3], v[194:195], v[194:195], v[2:3]
	v_pk_fma_f32 v[2:3], v[196:197], v[196:197], v[2:3]
	v_pk_mul_f32 v[252:253], v[190:191], v[160:161]
	v_cvt_pk_bf16_f32 v176, v252, v253
	v_pk_mul_f32 v[252:253], v[192:193], v[162:163]
	v_cvt_pk_bf16_f32 v177, v252, v253
	v_pk_mul_f32 v[252:253], v[194:195], v[156:157]
	v_cvt_pk_bf16_f32 v178, v252, v253
	v_pk_mul_f32 v[252:253], v[196:197], v[158:159]
	v_cvt_pk_bf16_f32 v179, v252, v253
	s_nop 1
	v_permlane16_swap_b32_e32 v176, v178
	v_permlane16_swap_b32_e32 v177, v179
	global_store_dwordx4 v165, v[176:179], s[92:93] offset:256
	v_add_f32_e32 v2, v2, v3
	v_mov_b32_e32 v0, v2
	s_nop 1
	v_permlane16_swap_b32_e32 v2, v0
	v_add_f32_e32 v2, v2, v0
	v_mov_b32_e32 v0, v2
	s_nop 1
	v_permlane32_swap_b32_e32 v2, v0
	v_add_f32_e32 v2, v2, v0
	v_lshrrev_b32_e32 v252, 12, v164
	v_lshlrev_b32_e32 v252, 2, v252
	s_mov_b64 exec, 0xffff
	global_atomic_add_f32 v252, v2, s[8:9]
	s_mov_b64 exec, -1
	v_add_u32_e32 v164, 0x10000, v164
	v_add_u32_e32 v165, 0x8000, v165
	v_mov_b32_e32 v2, 0
	v_mov_b32_e32 v3, 0
	s_waitcnt vmcnt(17)
	v_pk_fma_f32 v[198:199], v[132:133], v[72:73], v[198:199]
	v_pk_fma_f32 v[200:201], v[134:135], v[74:75], v[200:201]
	v_pk_fma_f32 v[202:203], v[128:129], v[76:77], v[202:203]
	v_pk_fma_f32 v[204:205], v[130:131], v[78:79], v[204:205]
	global_store_dwordx4 v164, v[198:201], s[2:3] offset:0
	global_store_dwordx4 v164, v[202:205], s[2:3] offset:64
	global_load_dwordx4 v[132:135], v175, s[2:3] offset:0
	global_load_dwordx4 v[128:131], v175, s[2:3] offset:64
	v_pk_fma_f32 v[2:3], v[198:199], v[198:199], v[2:3]
	v_pk_fma_f32 v[2:3], v[200:201], v[200:201], v[2:3]
	v_pk_fma_f32 v[2:3], v[202:203], v[202:203], v[2:3]
	v_pk_fma_f32 v[2:3], v[204:205], v[204:205], v[2:3]
	v_pk_mul_f32 v[252:253], v[198:199], v[170:171]
	v_cvt_pk_bf16_f32 v176, v252, v253
	v_pk_mul_f32 v[252:253], v[200:201], v[172:173]
	v_cvt_pk_bf16_f32 v177, v252, v253
	v_pk_mul_f32 v[252:253], v[202:203], v[166:167]
	v_cvt_pk_bf16_f32 v178, v252, v253
	v_pk_mul_f32 v[252:253], v[204:205], v[168:169]
	v_cvt_pk_bf16_f32 v179, v252, v253
	s_nop 1
	v_permlane16_swap_b32_e32 v176, v178
	v_permlane16_swap_b32_e32 v177, v179
	global_store_dwordx4 v165, v[176:179], s[92:93] offset:0
	s_waitcnt vmcnt(20)
; __device__ __forceinline__ unsigned cvt_pk_bf16(float lo, float hi) { unsigned r; asm volatile("v_cvt_pk_bf16_f32 %0, %1, %2" : "=v"(r) : "v"(lo), "v"(hi)); return r; }
;     __device__ __forceinline__ void operator()(const f32x4 (&acc)[2][2][4][2], const Unit& u, int wr, int wc, int fr, int fq) const {
;     ...
;             for (int m = 0; m < 4; ++m) { const size_t row = rowb + ai * HALF + m * 16; const size_t off = row * 1024 + col0; float s = 0.f;
; #pragma unroll
;                 for (int bj = 0; bj < 2; ++bj) { u32x2 w[2];
; #pragma unroll
;                     for (int n = 0; n < 2; ++n) { const f32x4 xv = *(const __attribute__((address_space(1))) f32x4*)(xin + off + bj * HALF + n * 16);
;                         const f32x4 xn = xv + gv[bj][n] * acc[ai][bj][m][n];
;                         *(__attribute__((address_space(1))) f32x4*)(out + off + bj * HALF + n * 16) = xn;
;                         if (XG) { s += (xn[0] * xn[0] + xn[1] * xn[1]) + (xn[2] * xn[2] + xn[3] * xn[3]); const f32x4 t = xn * Gv[bj][n];
;                             w[n].x = cvt_pk_bf16(t[0], t[1]); w[n].y = cvt_pk_bf16(t[2], t[3]); } }
;                     if (XG) {
;                         const bool odd = (fq & 1) != 0; const u32x2 snd = odd ? w[0] : w[1]; u32x2 rcv; rcv.x = __shfl_xor(snd.x, 16); rcv.y = __shfl_xor(snd.y, 16);
;                         u32x4 o4; if (odd) { o4.x = rcv.x; o4.y = rcv.y; o4.z = w[1].x; o4.w = w[1].y; } else { o4.x = w[0].x; o4.y = w[0].y; o4.z = rcv.x; o4.w = rcv.y; }
;                         *(u32x4*)(XG + off + bj * HALF + (odd ? 12 : 0)) = o4; } }
;                 if (XG) { s += __shfl_xor(s, 16); s += __shfl_xor(s, 32); if (fq == 0) atomicAdd(ssq + row, s); } }
	v_pk_fma_f32 v[236:237], v[124:125], v[60:61], v[236:237]
	v_pk_fma_f32 v[238:239], v[126:127], v[62:63], v[238:239]
	v_pk_fma_f32 v[240:241], v[120:121], v[56:57], v[240:241]
	v_pk_fma_f32 v[242:243], v[122:123], v[58:59], v[242:243]
	global_store_dwordx4 v164, v[236:239], s[2:3] offset:512
	global_store_dwordx4 v164, v[240:243], s[2:3] offset:576
	global_load_dwordx4 v[124:127], v175, s[2:3] offset:512
	global_load_dwordx4 v[120:123], v175, s[2:3] offset:576
	v_add_u32_e32 v175, 0x10000, v175
	v_pk_fma_f32 v[2:3], v[236:237], v[236:237], v[2:3]
	v_pk_fma_f32 v[2:3], v[238:239], v[238:239], v[2:3]
	v_pk_fma_f32 v[2:3], v[240:241], v[240:241], v[2:3]
	v_pk_fma_f32 v[2:3], v[242:243], v[242:243], v[2:3]
	v_pk_mul_f32 v[252:253], v[236:237], v[160:161]
	v_cvt_pk_bf16_f32 v176, v252, v253
	v_pk_mul_f32 v[252:253], v[238:239], v[162:163]
	v_cvt_pk_bf16_f32 v177, v252, v253
	v_pk_mul_f32 v[252:253], v[240:241], v[156:157]
	v_cvt_pk_bf16_f32 v178, v252, v253
	v_pk_mul_f32 v[252:253], v[242:243], v[158:159]
	v_cvt_pk_bf16_f32 v179, v252, v253
	s_nop 1
	v_permlane16_swap_b32_e32 v176, v178
	v_permlane16_swap_b32_e32 v177, v179
	global_store_dwordx4 v165, v[176:179], s[92:93] offset:256
	v_add_f32_e32 v2, v2, v3
	v_mov_b32_e32 v0, v2
	s_nop 1
	v_permlane16_swap_b32_e32 v2, v0
	v_add_f32_e32 v2, v2, v0
	v_mov_b32_e32 v0, v2
	s_nop 1
	v_permlane32_swap_b32_e32 v2, v0
	v_add_f32_e32 v2, v2, v0
	v_lshrrev_b32_e32 v252, 12, v164
	v_lshlrev_b32_e32 v252, 2, v252
	s_mov_b64 exec, 0xffff
	global_atomic_add_f32 v252, v2, s[8:9]
	s_mov_b64 exec, -1
	v_add_u32_e32 v164, 0x10000, v164
	v_add_u32_e32 v165, 0x8000, v165
	v_mov_b32_e32 v2, 0
	v_mov_b32_e32 v3, 0
	s_waitcnt vmcnt(24)
	v_pk_fma_f32 v[244:245], v[116:117], v[72:73], v[244:245]
	v_pk_fma_f32 v[246:247], v[118:119], v[74:75], v[246:247]
	v_pk_fma_f32 v[248:249], v[112:113], v[76:77], v[248:249]
	v_pk_fma_f32 v[250:251], v[114:115], v[78:79], v[250:251]
	global_store_dwordx4 v164, v[244:247], s[2:3] offset:0
	global_store_dwordx4 v164, v[248:251], s[2:3] offset:64
	global_load_dwordx4 v[116:119], v175, s[2:3] offset:0
	global_load_dwordx4 v[112:115], v175, s[2:3] offset:64
	v_pk_fma_f32 v[2:3], v[244:245], v[244:245], v[2:3]
	v_pk_fma_f32 v[2:3], v[246:247], v[246:247], v[2:3]
	v_pk_fma_f32 v[2:3], v[248:249], v[248:249], v[2:3]
	v_pk_fma_f32 v[2:3], v[250:251], v[250:251], v[2:3]
	v_pk_mul_f32 v[252:253], v[244:245], v[170:171]
	v_cvt_pk_bf16_f32 v176, v252, v253
	v_pk_mul_f32 v[252:253], v[246:247], v[172:173]
	v_cvt_pk_bf16_f32 v177, v252, v253
	v_pk_mul_f32 v[252:253], v[248:249], v[166:167]
	v_cvt_pk_bf16_f32 v178, v252, v253
	v_pk_mul_f32 v[252:253], v[250:251], v[168:169]
	v_cvt_pk_bf16_f32 v179, v252, v253
	s_nop 1
	v_permlane16_swap_b32_e32 v176, v178
	v_permlane16_swap_b32_e32 v177, v179
	global_store_dwordx4 v165, v[176:179], s[92:93] offset:0
	s_waitcnt vmcnt(27)
	v_pk_fma_f32 v[206:207], v[108:109], v[60:61], v[206:207]
	v_pk_fma_f32 v[208:209], v[110:111], v[62:63], v[208:209]
	v_pk_fma_f32 v[210:211], v[104:105], v[56:57], v[210:211]
	v_pk_fma_f32 v[212:213], v[106:107], v[58:59], v[212:213]
	global_store_dwordx4 v164, v[206:209], s[2:3] offset:512
	global_store_dwordx4 v164, v[210:213], s[2:3] offset:576
	global_load_dwordx4 v[108:111], v175, s[2:3] offset:512
	global_load_dwordx4 v[104:107], v175, s[2:3] offset:576
	v_add_u32_e32 v175, 0x10000, v175
	v_pk_fma_f32 v[2:3], v[206:207], v[206:207], v[2:3]
	v_pk_fma_f32 v[2:3], v[208:209], v[208:209], v[2:3]
	v_pk_fma_f32 v[2:3], v[210:211], v[210:211], v[2:3]
	v_pk_fma_f32 v[2:3], v[212:213], v[212:213], v[2:3]
	v_pk_mul_f32 v[252:253], v[206:207], v[160:161]
	v_cvt_pk_bf16_f32 v176, v252, v253
	v_pk_mul_f32 v[252:253], v[208:209], v[162:163]
	v_cvt_pk_bf16_f32 v177, v252, v253
	v_pk_mul_f32 v[252:253], v[210:211], v[156:157]
	v_cvt_pk_bf16_f32 v178, v252, v253
	v_pk_mul_f32 v[252:253], v[212:213], v[158:159]
	v_cvt_pk_bf16_f32 v179, v252, v253
	s_nop 1
	v_permlane16_swap_b32_e32 v176, v178
	v_permlane16_swap_b32_e32 v177, v179
	global_store_dwordx4 v165, v[176:179], s[92:93] offset:256
	v_add_f32_e32 v2, v2, v3
	v_mov_b32_e32 v0, v2
	s_nop 1
	v_permlane16_swap_b32_e32 v2, v0
	v_add_f32_e32 v2, v2, v0
	v_mov_b32_e32 v0, v2
	s_nop 1
	v_permlane32_swap_b32_e32 v2, v0
	v_add_f32_e32 v2, v2, v0
	v_lshrrev_b32_e32 v252, 12, v164
	v_lshlrev_b32_e32 v252, 2, v252
	s_mov_b64 exec, 0xffff
	global_atomic_add_f32 v252, v2, s[8:9]
	s_mov_b64 exec, -1
	v_add_u32_e32 v164, 0x10000, v164
	v_add_u32_e32 v165, 0x8000, v165
	v_mov_b32_e32 v2, 0
	v_mov_b32_e32 v3, 0
	s_waitcnt vmcnt(29)
	v_pk_fma_f32 v[64:65], v[100:101], v[72:73], v[64:65]
	v_pk_fma_f32 v[66:67], v[102:103], v[74:75], v[66:67]
	v_pk_fma_f32 v[144:145], v[96:97], v[76:77], v[144:145]
	v_pk_fma_f32 v[146:147], v[98:99], v[78:79], v[146:147]
	global_store_dwordx4 v164, v[64:67], s[2:3] offset:0
	global_store_dwordx4 v164, v[144:147], s[2:3] offset:64
	global_load_dwordx4 v[100:103], v175, s[2:3] offset:0
	global_load_dwordx4 v[96:99], v175, s[2:3] offset:64
	v_pk_fma_f32 v[2:3], v[64:65], v[64:65], v[2:3]
	v_pk_fma_f32 v[2:3], v[66:67], v[66:67], v[2:3]
	v_pk_fma_f32 v[2:3], v[144:145], v[144:145], v[2:3]
	v_pk_fma_f32 v[2:3], v[146:147], v[146:147], v[2:3]
	v_pk_mul_f32 v[252:253], v[64:65], v[170:171]
	v_cvt_pk_bf16_f32 v176, v252, v253
	v_pk_mul_f32 v[252:253], v[66:67], v[172:173]
	v_cvt_pk_bf16_f32 v177, v252, v253
	v_pk_mul_f32 v[252:253], v[144:145], v[166:167]
	v_cvt_pk_bf16_f32 v178, v252, v253
	v_pk_mul_f32 v[252:253], v[146:147], v[168:169]
	v_cvt_pk_bf16_f32 v179, v252, v253
	s_nop 1
	v_permlane16_swap_b32_e32 v176, v178
	v_permlane16_swap_b32_e32 v177, v179
	global_store_dwordx4 v165, v[176:179], s[92:93] offset:0
	s_waitcnt vmcnt(29)
; __device__ __forceinline__ unsigned cvt_pk_bf16(float lo, float hi) { unsigned r; asm volatile("v_cvt_pk_bf16_f32 %0, %1, %2" : "=v"(r) : "v"(lo), "v"(hi)); return r; }
;     __device__ __forceinline__ void operator()(const f32x4 (&acc)[2][2][4][2], const Unit& u, int wr, int wc, int fr, int fq) const {
;     ...
;             for (int m = 0; m < 4; ++m) { const size_t row = rowb + ai * HALF + m * 16; const size_t off = row * 1024 + col0; float s = 0.f;
; #pragma unroll
;                 for (int bj = 0; bj < 2; ++bj) { u32x2 w[2];
; #pragma unroll
;                     for (int n = 0; n < 2; ++n) { const f32x4 xv = *(const __attribute__((address_space(1))) f32x4*)(xin + off + bj * HALF + n * 16);
;                         const f32x4 xn = xv + gv[bj][n] * acc[ai][bj][m][n];
;                         *(__attribute__((address_space(1))) f32x4*)(out + off + bj * HALF + n * 16) = xn;
;                         if (XG) { s += (xn[0] * xn[0] + xn[1] * xn[1]) + (xn[2] * xn[2] + xn[3] * xn[3]); const f32x4 t = xn * Gv[bj][n];
;                             w[n].x = cvt_pk_bf16(t[0], t[1]); w[n].y = cvt_pk_bf16(t[2], t[3]); } }
;                     if (XG) {
;                         const bool odd = (fq & 1) != 0; const u32x2 snd = odd ? w[0] : w[1]; u32x2 rcv; rcv.x = __shfl_xor(snd.x, 16); rcv.y = __shfl_xor(snd.y, 16);
;                         u32x4 o4; if (odd) { o4.x = rcv.x; o4.y = rcv.y; o4.z = w[1].x; o4.w = w[1].y; } else { o4.x = w[0].x; o4.y = w[0].y; o4.z = rcv.x; o4.w = rcv.y; }
;                         *(u32x4*)(XG + off + bj * HALF + (odd ? 12 : 0)) = o4; } }
;                 if (XG) { s += __shfl_xor(s, 16); s += __shfl_xor(s, 32); if (fq == 0) atomicAdd(ssq + row, s); } }
	v_pk_fma_f32 v[140:141], v[92:93], v[60:61], v[140:141]
	v_pk_fma_f32 v[142:143], v[94:95], v[62:63], v[142:143]
	v_pk_fma_f32 v[136:137], v[88:89], v[56:57], v[136:137]
	v_pk_fma_f32 v[138:139], v[90:91], v[58:59], v[138:139]
	global_store_dwordx4 v164, v[140:143], s[2:3] offset:512
	global_store_dwordx4 v164, v[136:139], s[2:3] offset:576
	global_load_dwordx4 v[92:95], v175, s[2:3] offset:512
	global_load_dwordx4 v[88:91], v175, s[2:3] offset:576
	v_add_u32_e32 v175, 0x10000, v175
	v_pk_fma_f32 v[2:3], v[140:141], v[140:141], v[2:3]
	v_pk_fma_f32 v[2:3], v[142:143], v[142:143], v[2:3]
	v_pk_fma_f32 v[2:3], v[136:137], v[136:137], v[2:3]
	v_pk_fma_f32 v[2:3], v[138:139], v[138:139], v[2:3]
	v_pk_mul_f32 v[252:253], v[140:141], v[160:161]
	v_cvt_pk_bf16_f32 v176, v252, v253
	v_pk_mul_f32 v[252:253], v[142:143], v[162:163]
	v_cvt_pk_bf16_f32 v177, v252, v253
	v_pk_mul_f32 v[252:253], v[136:137], v[156:157]
	v_cvt_pk_bf16_f32 v178, v252, v253
	v_pk_mul_f32 v[252:253], v[138:139], v[158:159]
	v_cvt_pk_bf16_f32 v179, v252, v253
	s_nop 1
	v_permlane16_swap_b32_e32 v176, v178
	v_permlane16_swap_b32_e32 v177, v179
	global_store_dwordx4 v165, v[176:179], s[92:93] offset:256
	v_add_f32_e32 v2, v2, v3
	v_mov_b32_e32 v0, v2
	s_nop 1
	v_permlane16_swap_b32_e32 v2, v0
	v_add_f32_e32 v2, v2, v0
	v_mov_b32_e32 v0, v2
	s_nop 1
	v_permlane32_swap_b32_e32 v2, v0
	v_add_f32_e32 v2, v2, v0
	v_lshrrev_b32_e32 v252, 12, v164
	v_lshlrev_b32_e32 v252, 2, v252
	s_mov_b64 exec, 0xffff
	global_atomic_add_f32 v252, v2, s[8:9]
	s_mov_b64 exec, -1
	v_add_u32_e32 v164, 0x50000, v164
	v_add_u32_e32 v165, 0x28000, v165
	v_mov_b32_e32 v2, 0
	v_mov_b32_e32 v3, 0
	s_waitcnt vmcnt(29)
	v_pk_fma_f32 v[132:133], v[84:85], v[72:73], v[132:133]
	v_pk_fma_f32 v[134:135], v[86:87], v[74:75], v[134:135]
	v_pk_fma_f32 v[128:129], v[80:81], v[76:77], v[128:129]
	v_pk_fma_f32 v[130:131], v[82:83], v[78:79], v[130:131]
	global_store_dwordx4 v164, v[132:135], s[2:3] offset:0
	global_store_dwordx4 v164, v[128:131], s[2:3] offset:64
	global_load_dwordx4 v[84:87], v175, s[2:3] offset:0
	global_load_dwordx4 v[80:83], v175, s[2:3] offset:64
	v_pk_fma_f32 v[2:3], v[132:133], v[132:133], v[2:3]
	v_pk_fma_f32 v[2:3], v[134:135], v[134:135], v[2:3]
	v_pk_fma_f32 v[2:3], v[128:129], v[128:129], v[2:3]
	v_pk_fma_f32 v[2:3], v[130:131], v[130:131], v[2:3]
	v_pk_mul_f32 v[252:253], v[132:133], v[170:171]
	v_cvt_pk_bf16_f32 v176, v252, v253
	v_pk_mul_f32 v[252:253], v[134:135], v[172:173]
	v_cvt_pk_bf16_f32 v177, v252, v253
	v_pk_mul_f32 v[252:253], v[128:129], v[166:167]
	v_cvt_pk_bf16_f32 v178, v252, v253
	v_pk_mul_f32 v[252:253], v[130:131], v[168:169]
	v_cvt_pk_bf16_f32 v179, v252, v253
	s_nop 1
	v_permlane16_swap_b32_e32 v176, v178
	v_permlane16_swap_b32_e32 v177, v179
	global_store_dwordx4 v165, v[176:179], s[92:93] offset:0
	s_waitcnt vmcnt(29)
	v_pk_fma_f32 v[124:125], v[68:69], v[60:61], v[124:125]
	v_pk_fma_f32 v[126:127], v[70:71], v[62:63], v[126:127]
	v_pk_fma_f32 v[120:121], v[52:53], v[56:57], v[120:121]
	v_pk_fma_f32 v[122:123], v[54:55], v[58:59], v[122:123]
	global_store_dwordx4 v164, v[124:127], s[2:3] offset:512
	global_store_dwordx4 v164, v[120:123], s[2:3] offset:576
	global_load_dwordx4 v[68:71], v175, s[2:3] offset:512
	global_load_dwordx4 v[52:55], v175, s[2:3] offset:576
	v_pk_fma_f32 v[2:3], v[124:125], v[124:125], v[2:3]
	v_pk_fma_f32 v[2:3], v[126:127], v[126:127], v[2:3]
	v_pk_fma_f32 v[2:3], v[120:121], v[120:121], v[2:3]
	v_pk_fma_f32 v[2:3], v[122:123], v[122:123], v[2:3]
	v_pk_mul_f32 v[252:253], v[124:125], v[160:161]
	v_cvt_pk_bf16_f32 v176, v252, v253
	v_pk_mul_f32 v[252:253], v[126:127], v[162:163]
	v_cvt_pk_bf16_f32 v177, v252, v253
	v_pk_mul_f32 v[252:253], v[120:121], v[156:157]
	v_cvt_pk_bf16_f32 v178, v252, v253
	v_pk_mul_f32 v[252:253], v[122:123], v[158:159]
	v_cvt_pk_bf16_f32 v179, v252, v253
	s_nop 1
	v_permlane16_swap_b32_e32 v176, v178
	v_permlane16_swap_b32_e32 v177, v179
	global_store_dwordx4 v165, v[176:179], s[92:93] offset:256
	v_add_f32_e32 v2, v2, v3
	v_mov_b32_e32 v0, v2
	s_nop 1
	v_permlane16_swap_b32_e32 v2, v0
	v_add_f32_e32 v2, v2, v0
	v_mov_b32_e32 v0, v2
	s_nop 1
	v_permlane32_swap_b32_e32 v2, v0
	v_add_f32_e32 v2, v2, v0
	v_lshrrev_b32_e32 v252, 12, v164
	v_lshlrev_b32_e32 v252, 2, v252
	s_mov_b64 exec, 0xffff
	global_atomic_add_f32 v252, v2, s[8:9]
	s_mov_b64 exec, -1
	v_add_u32_e32 v164, 0x10000, v164
	v_add_u32_e32 v165, 0x8000, v165
	v_mov_b32_e32 v2, 0
	v_mov_b32_e32 v3, 0
	s_waitcnt vmcnt(29)
	v_pk_fma_f32 v[116:117], v[48:49], v[72:73], v[116:117]
	v_pk_fma_f32 v[118:119], v[50:51], v[74:75], v[118:119]
	v_pk_fma_f32 v[112:113], v[44:45], v[76:77], v[112:113]
	v_pk_fma_f32 v[114:115], v[46:47], v[78:79], v[114:115]
	global_store_dwordx4 v164, v[116:119], s[2:3] offset:0
	global_store_dwordx4 v164, v[112:115], s[2:3] offset:64
	v_pk_fma_f32 v[2:3], v[116:117], v[116:117], v[2:3]
	v_pk_fma_f32 v[2:3], v[118:119], v[118:119], v[2:3]
	v_pk_fma_f32 v[2:3], v[112:113], v[112:113], v[2:3]
	v_pk_fma_f32 v[2:3], v[114:115], v[114:115], v[2:3]
	v_pk_mul_f32 v[252:253], v[116:117], v[170:171]
	v_cvt_pk_bf16_f32 v176, v252, v253
	v_pk_mul_f32 v[252:253], v[118:119], v[172:173]
	v_cvt_pk_bf16_f32 v177, v252, v253
	v_pk_mul_f32 v[252:253], v[112:113], v[166:167]
	v_cvt_pk_bf16_f32 v178, v252, v253
	v_pk_mul_f32 v[252:253], v[114:115], v[168:169]
	v_cvt_pk_bf16_f32 v179, v252, v253
	s_nop 1
	v_permlane16_swap_b32_e32 v176, v178
	v_permlane16_swap_b32_e32 v177, v179
	global_store_dwordx4 v165, v[176:179], s[92:93] offset:0
	s_waitcnt vmcnt(27)
; __device__ __forceinline__ unsigned cvt_pk_bf16(float lo, float hi) { unsigned r; asm volatile("v_cvt_pk_bf16_f32 %0, %1, %2" : "=v"(r) : "v"(lo), "v"(hi)); return r; }
;     __device__ __forceinline__ void operator()(const f32x4 (&acc)[2][2][4][2], const Unit& u, int wr, int wc, int fr, int fq) const {
;     ...
;             for (int m = 0; m < 4; ++m) { const size_t row = rowb + ai * HALF + m * 16; const size_t off = row * 1024 + col0; float s = 0.f;
; #pragma unroll
;                 for (int bj = 0; bj < 2; ++bj) { u32x2 w[2];
; #pragma unroll
;                     for (int n = 0; n < 2; ++n) { const f32x4 xv = *(const __attribute__((address_space(1))) f32x4*)(xin + off + bj * HALF + n * 16);
;                         const f32x4 xn = xv + gv[bj][n] * acc[ai][bj][m][n];
;                         *(__attribute__((address_space(1))) f32x4*)(out + off + bj * HALF + n * 16) = xn;
;                         if (XG) { s += (xn[0] * xn[0] + xn[1] * xn[1]) + (xn[2] * xn[2] + xn[3] * xn[3]); const f32x4 t = xn * Gv[bj][n];
;                             w[n].x = cvt_pk_bf16(t[0], t[1]); w[n].y = cvt_pk_bf16(t[2], t[3]); } }
;                     if (XG) {
;                         const bool odd = (fq & 1) != 0; const u32x2 snd = odd ? w[0] : w[1]; u32x2 rcv; rcv.x = __shfl_xor(snd.x, 16); rcv.y = __shfl_xor(snd.y, 16);
;                         u32x4 o4; if (odd) { o4.x = rcv.x; o4.y = rcv.y; o4.z = w[1].x; o4.w = w[1].y; } else { o4.x = w[0].x; o4.y = w[0].y; o4.z = rcv.x; o4.w = rcv.y; }
;                         *(u32x4*)(XG + off + bj * HALF + (odd ? 12 : 0)) = o4; } }
;                 if (XG) { s += __shfl_xor(s, 16); s += __shfl_xor(s, 32); if (fq == 0) atomicAdd(ssq + row, s); } }
	v_pk_fma_f32 v[108:109], v[40:41], v[60:61], v[108:109]
	v_pk_fma_f32 v[110:111], v[42:43], v[62:63], v[110:111]
	v_pk_fma_f32 v[104:105], v[36:37], v[56:57], v[104:105]
	v_pk_fma_f32 v[106:107], v[38:39], v[58:59], v[106:107]
	global_store_dwordx4 v164, v[108:111], s[2:3] offset:512
	global_store_dwordx4 v164, v[104:107], s[2:3] offset:576
	v_pk_fma_f32 v[2:3], v[108:109], v[108:109], v[2:3]
	v_pk_fma_f32 v[2:3], v[110:111], v[110:111], v[2:3]
	v_pk_fma_f32 v[2:3], v[104:105], v[104:105], v[2:3]
	v_pk_fma_f32 v[2:3], v[106:107], v[106:107], v[2:3]
	v_pk_mul_f32 v[252:253], v[108:109], v[160:161]
	v_cvt_pk_bf16_f32 v176, v252, v253
	v_pk_mul_f32 v[252:253], v[110:111], v[162:163]
	v_cvt_pk_bf16_f32 v177, v252, v253
	v_pk_mul_f32 v[252:253], v[104:105], v[156:157]
	v_cvt_pk_bf16_f32 v178, v252, v253
	v_pk_mul_f32 v[252:253], v[106:107], v[158:159]
	v_cvt_pk_bf16_f32 v179, v252, v253
	s_nop 1
	v_permlane16_swap_b32_e32 v176, v178
	v_permlane16_swap_b32_e32 v177, v179
	global_store_dwordx4 v165, v[176:179], s[92:93] offset:256
	v_add_f32_e32 v2, v2, v3
	v_mov_b32_e32 v0, v2
	s_nop 1
	v_permlane16_swap_b32_e32 v2, v0
	v_add_f32_e32 v2, v2, v0
	v_mov_b32_e32 v0, v2
	s_nop 1
	v_permlane32_swap_b32_e32 v2, v0
	v_add_f32_e32 v2, v2, v0
	v_lshrrev_b32_e32 v252, 12, v164
	v_lshlrev_b32_e32 v252, 2, v252
	s_mov_b64 exec, 0xffff
	global_atomic_add_f32 v252, v2, s[8:9]
	s_mov_b64 exec, -1
	v_add_u32_e32 v164, 0x10000, v164
	v_add_u32_e32 v165, 0x8000, v165
	v_mov_b32_e32 v2, 0
	v_mov_b32_e32 v3, 0
	s_waitcnt vmcnt(25)
	v_pk_fma_f32 v[100:101], v[32:33], v[72:73], v[100:101]
	v_pk_fma_f32 v[102:103], v[34:35], v[74:75], v[102:103]
	v_pk_fma_f32 v[96:97], v[28:29], v[76:77], v[96:97]
	v_pk_fma_f32 v[98:99], v[30:31], v[78:79], v[98:99]
	global_store_dwordx4 v164, v[100:103], s[2:3] offset:0
	global_store_dwordx4 v164, v[96:99], s[2:3] offset:64
	v_pk_fma_f32 v[2:3], v[100:101], v[100:101], v[2:3]
	v_pk_fma_f32 v[2:3], v[102:103], v[102:103], v[2:3]
	v_pk_fma_f32 v[2:3], v[96:97], v[96:97], v[2:3]
	v_pk_fma_f32 v[2:3], v[98:99], v[98:99], v[2:3]
	v_pk_mul_f32 v[252:253], v[100:101], v[170:171]
	v_cvt_pk_bf16_f32 v176, v252, v253
	v_pk_mul_f32 v[252:253], v[102:103], v[172:173]
	v_cvt_pk_bf16_f32 v177, v252, v253
	v_pk_mul_f32 v[252:253], v[96:97], v[166:167]
	v_cvt_pk_bf16_f32 v178, v252, v253
	v_pk_mul_f32 v[252:253], v[98:99], v[168:169]
	v_cvt_pk_bf16_f32 v179, v252, v253
	s_nop 1
	v_permlane16_swap_b32_e32 v176, v178
	v_permlane16_swap_b32_e32 v177, v179
	global_store_dwordx4 v165, v[176:179], s[92:93] offset:0
	s_waitcnt vmcnt(23)
	v_pk_fma_f32 v[92:93], v[24:25], v[60:61], v[92:93]
	v_pk_fma_f32 v[94:95], v[26:27], v[62:63], v[94:95]
	v_pk_fma_f32 v[88:89], v[20:21], v[56:57], v[88:89]
	v_pk_fma_f32 v[90:91], v[22:23], v[58:59], v[90:91]
	global_store_dwordx4 v164, v[92:95], s[2:3] offset:512
	global_store_dwordx4 v164, v[88:91], s[2:3] offset:576
	v_pk_fma_f32 v[2:3], v[92:93], v[92:93], v[2:3]
	v_pk_fma_f32 v[2:3], v[94:95], v[94:95], v[2:3]
	v_pk_fma_f32 v[2:3], v[88:89], v[88:89], v[2:3]
	v_pk_fma_f32 v[2:3], v[90:91], v[90:91], v[2:3]
	v_pk_mul_f32 v[252:253], v[92:93], v[160:161]
	v_cvt_pk_bf16_f32 v176, v252, v253
	v_pk_mul_f32 v[252:253], v[94:95], v[162:163]
	v_cvt_pk_bf16_f32 v177, v252, v253
	v_pk_mul_f32 v[252:253], v[88:89], v[156:157]
	v_cvt_pk_bf16_f32 v178, v252, v253
	v_pk_mul_f32 v[252:253], v[90:91], v[158:159]
	v_cvt_pk_bf16_f32 v179, v252, v253
	s_nop 1
	v_permlane16_swap_b32_e32 v176, v178
	v_permlane16_swap_b32_e32 v177, v179
	global_store_dwordx4 v165, v[176:179], s[92:93] offset:256
	v_add_f32_e32 v2, v2, v3
	v_mov_b32_e32 v0, v2
	s_nop 1
	v_permlane16_swap_b32_e32 v2, v0
	v_add_f32_e32 v2, v2, v0
	v_mov_b32_e32 v0, v2
	s_nop 1
	v_permlane32_swap_b32_e32 v2, v0
	v_add_f32_e32 v2, v2, v0
	v_lshrrev_b32_e32 v252, 12, v164
	v_lshlrev_b32_e32 v252, 2, v252
	s_mov_b64 exec, 0xffff
	global_atomic_add_f32 v252, v2, s[8:9]
	s_mov_b64 exec, -1
	v_add_u32_e32 v164, 0x10000, v164
	v_add_u32_e32 v165, 0x8000, v165
	v_mov_b32_e32 v2, 0
	v_mov_b32_e32 v3, 0
	s_waitcnt vmcnt(21)
	v_pk_fma_f32 v[84:85], v[16:17], v[72:73], v[84:85]
	v_pk_fma_f32 v[86:87], v[18:19], v[74:75], v[86:87]
	v_pk_fma_f32 v[80:81], v[12:13], v[76:77], v[80:81]
	v_pk_fma_f32 v[82:83], v[14:15], v[78:79], v[82:83]
	global_store_dwordx4 v164, v[84:87], s[2:3] offset:0
	global_store_dwordx4 v164, v[80:83], s[2:3] offset:64
	v_pk_fma_f32 v[2:3], v[84:85], v[84:85], v[2:3]
	v_pk_fma_f32 v[2:3], v[86:87], v[86:87], v[2:3]
	v_pk_fma_f32 v[2:3], v[80:81], v[80:81], v[2:3]
	v_pk_fma_f32 v[2:3], v[82:83], v[82:83], v[2:3]
	v_pk_mul_f32 v[252:253], v[84:85], v[170:171]
	v_cvt_pk_bf16_f32 v176, v252, v253
	v_pk_mul_f32 v[252:253], v[86:87], v[172:173]
	v_cvt_pk_bf16_f32 v177, v252, v253
	v_pk_mul_f32 v[252:253], v[80:81], v[166:167]
	v_cvt_pk_bf16_f32 v178, v252, v253
	v_pk_mul_f32 v[252:253], v[82:83], v[168:169]
	v_cvt_pk_bf16_f32 v179, v252, v253
	s_nop 1
	v_permlane16_swap_b32_e32 v176, v178
	v_permlane16_swap_b32_e32 v177, v179
	global_store_dwordx4 v165, v[176:179], s[92:93] offset:0
	s_waitcnt vmcnt(19)
	v_pk_fma_f32 v[68:69], v[8:9], v[60:61], v[68:69]
	v_pk_fma_f32 v[70:71], v[10:11], v[62:63], v[70:71]
	v_pk_fma_f32 v[52:53], v[4:5], v[56:57], v[52:53]
	v_pk_fma_f32 v[54:55], v[6:7], v[58:59], v[54:55]
	global_store_dwordx4 v164, v[68:71], s[2:3] offset:512
	global_store_dwordx4 v164, v[52:55], s[2:3] offset:576
	v_pk_fma_f32 v[2:3], v[68:69], v[68:69], v[2:3]
	v_pk_fma_f32 v[2:3], v[70:71], v[70:71], v[2:3]
	v_pk_fma_f32 v[2:3], v[52:53], v[52:53], v[2:3]
	v_pk_fma_f32 v[2:3], v[54:55], v[54:55], v[2:3]
	v_pk_mul_f32 v[252:253], v[68:69], v[160:161]
	v_cvt_pk_bf16_f32 v176, v252, v253
	v_pk_mul_f32 v[252:253], v[70:71], v[162:163]
	v_cvt_pk_bf16_f32 v177, v252, v253
	v_pk_mul_f32 v[252:253], v[52:53], v[156:157]
	v_cvt_pk_bf16_f32 v178, v252, v253
	v_pk_mul_f32 v[252:253], v[54:55], v[158:159]
	v_cvt_pk_bf16_f32 v179, v252, v253
	s_nop 1
	v_permlane16_swap_b32_e32 v176, v178
	v_permlane16_swap_b32_e32 v177, v179
	global_store_dwordx4 v165, v[176:179], s[92:93] offset:256
	v_add_f32_e32 v2, v2, v3
	v_mov_b32_e32 v0, v2
	s_nop 1
	v_permlane16_swap_b32_e32 v2, v0
	v_add_f32_e32 v2, v2, v0
	v_mov_b32_e32 v0, v2
	s_nop 1
	v_permlane32_swap_b32_e32 v2, v0
	v_add_f32_e32 v2, v2, v0
	v_lshrrev_b32_e32 v252, 12, v164
	v_lshlrev_b32_e32 v252, 2, v252
	s_mov_b64 exec, 0xffff
	global_atomic_add_f32 v252, v2, s[8:9]
	s_mov_b64 exec, -1
	s_branch .LBB0_823
